# barrier leaders: no TOPGEN bump for the last leader and no wait for the XGEN bump (global atomic, fire and forget)
# baseline (speedup 1.0000x reference)
.LBB0_194:
	s_andn2_saveexec_b64 s[4:5], s[4:5]
	s_cbranch_execz .LBB0_210
	s_add_i32 s101, s101, 1
	v_mov_b32_e32 v1, s36
	v_add_co_u32_e32 v2, vcc, 0x3000, v1
	v_mov_b32_e32 v1, s37
	buffer_wbl2 sc1
	s_waitcnt vmcnt(0)
	v_addc_co_u32_e32 v3, vcc, 0, v1, vcc
	v_mov_b32_e32 v1, 1
	flat_atomic_add v1, v[2:3], v1 offset:1024 sc0
	v_cvt_f32_u32_e32 v2, v0
	v_sub_u32_e32 v3, 0, v0
	s_add_u32 s4, s36, 0x3400
	s_addc_u32 s5, s37, 0
	v_rcp_iflag_f32_e32 v2, v2
	s_mov_b64 s[8:9], 0
	v_mul_f32_e32 v2, 0x4f7ffffe, v2
	v_cvt_u32_f32_e32 v2, v2
	v_mul_lo_u32 v3, v3, v2
	v_mul_hi_u32 v3, v2, v3
	v_add_u32_e32 v2, v2, v3
	s_waitcnt vmcnt(0) lgkmcnt(0)
	v_mul_hi_u32 v2, v1, v2
	v_mul_lo_u32 v4, v2, v0
	v_add_u32_e32 v3, 1, v1
	v_sub_u32_e32 v1, v1, v4
	v_add_u32_e32 v5, 1, v2
	v_cmp_ge_u32_e32 vcc, v1, v0
	v_sub_u32_e32 v4, v1, v0
	s_nop 0
	v_cndmask_b32_e32 v2, v2, v5, vcc
	v_cndmask_b32_e32 v1, v1, v4, vcc
	v_add_u32_e32 v4, 1, v2
	v_cmp_ge_u32_e32 vcc, v1, v0
	s_nop 1
	v_cndmask_b32_e32 v2, v2, v4, vcc
	v_mad_u64_u32 v[0:1], s[6:7], v0, v2, v[0:1]
	v_cmp_ne_u32_e32 vcc, v3, v0
	v_mov_b32_e32 v3, v0
	v_mov_b64_e32 v[0:1], s[4:5]
	s_and_saveexec_b64 s[6:7], vcc
	s_cbranch_execz .LBB0_207
	v_mov_b64_e32 v[0:1], s[4:5]
	flat_load_dword v0, v[0:1] sc1
	s_mov_b64 s[12:13], 0
	s_waitcnt vmcnt(0) lgkmcnt(0)
	v_cmp_lt_u32_e32 vcc, v0, v3
	s_and_saveexec_b64 s[10:11], vcc
	s_cbranch_execz .LBB0_206
	s_add_u32 s8, s36, 0x200
	s_addc_u32 s9, s37, 0
	s_mov_b32 s25, 1
	s_branch .LBB0_199

.LBB0_209:
	s_or_b64 exec, exec, s[4:5]
	s_add_i32 s4, s24, 0x900
	s_mov_b32 s5, 0
	s_lshl_b64 s[4:5], s[4:5], 2
	s_add_u32 s4, s36, s4
	s_addc_u32 s5, s37, s5
	v_mov_b32_e32 v2, 1
	v_mov_b64_e32 v[0:1], s[4:5]
	s_waitcnt vmcnt(0) lgkmcnt(0)
	s_nop 0
	global_atomic_add v[0:1], v2, off
	s_nop 0

.LBB0_211:
	s_or_b64 exec, exec, s[8:9]
	s_add_i32 s82, s6, 0x900
	s_lshl_b64 s[6:7], s[82:83], 2
	s_add_u32 s6, s42, s6
	s_addc_u32 s7, s43, s7
	v_mov_b64_e32 v[0:1], s[6:7]
	s_waitcnt vmcnt(0) lgkmcnt(0)
	buffer_inv sc1
	global_atomic_add v[0:1], v228, off
	s_nop 0

.LBB0_388:
	s_andn2_saveexec_b64 s[8:9], s[8:9]
	s_cbranch_execz .LBB0_404
	s_cmp_eq_u32 s100, 0
	s_cbranch_scc1 .Lfl_1
	s_add_i32 s82, s6, 0x900
	s_lshl_b64 s[10:11], s[82:83], 2
	s_add_u32 s10, s42, s10
	s_addc_u32 s11, s43, s11
	v_mov_b64_e32 v[0:1], s[10:11]
	buffer_inv sc1
	global_atomic_add v[0:1], v228, off
	s_nop 0
	s_branch .LBB0_404
.Lfl_1:
	s_add_i32 s101, s101, 1
	v_mov_b32_e32 v1, s42
	v_add_co_u32_e32 v2, vcc, 0x3000, v1
	v_mov_b32_e32 v1, s43
	buffer_wbl2 sc1
	s_waitcnt vmcnt(0)
	v_addc_co_u32_e32 v3, vcc, 0, v1, vcc
	flat_atomic_add v1, v[2:3], v228 offset:1024 sc0
	v_cvt_f32_u32_e32 v2, v0
	v_sub_u32_e32 v3, 0, v0
	s_mov_b64 s[12:13], 0
	v_rcp_iflag_f32_e32 v2, v2
	s_nop 0
	v_mul_f32_e32 v2, 0x4f7ffffe, v2
	v_cvt_u32_f32_e32 v2, v2
	v_mul_lo_u32 v3, v3, v2
	v_mul_hi_u32 v3, v2, v3
	v_add_u32_e32 v2, v2, v3
	s_waitcnt vmcnt(0) lgkmcnt(0)
	v_mul_hi_u32 v2, v1, v2
	v_mul_lo_u32 v3, v2, v0
	v_sub_u32_e32 v3, v1, v3
	v_cmp_ge_u32_e32 vcc, v3, v0
	v_add_u32_e32 v4, 1, v2
	s_nop 0
	v_cndmask_b32_e32 v2, v2, v4, vcc
	v_sub_u32_e32 v4, v3, v0
	v_cndmask_b32_e32 v3, v3, v4, vcc
	v_cmp_ge_u32_e32 vcc, v3, v0
	v_add_u32_e32 v3, 1, v2
	s_nop 0
	v_cndmask_b32_e32 v2, v2, v3, vcc
	v_add_u32_e32 v3, 1, v1
	v_mad_u64_u32 v[0:1], s[8:9], v0, v2, v[0:1]
	s_add_u32 s8, s42, 0x3400
	s_addc_u32 s9, s43, 0
	v_cmp_ne_u32_e32 vcc, v3, v0
	v_mov_b32_e32 v3, v0
	v_mov_b64_e32 v[0:1], s[8:9]
	s_and_saveexec_b64 s[10:11], vcc
	s_cbranch_execz .LBB0_401
	v_mov_b64_e32 v[0:1], s[8:9]
	flat_load_dword v0, v[0:1] sc1
	s_mov_b64 s[16:17], 0
	s_waitcnt vmcnt(0) lgkmcnt(0)
	v_cmp_lt_u32_e32 vcc, v0, v3
	s_and_saveexec_b64 s[14:15], vcc
	s_cbranch_execz .LBB0_400
	s_add_u32 s12, s42, 0x200
	s_addc_u32 s13, s43, 0
	s_mov_b32 s7, 1
	s_branch .LBB0_393

.LBB0_770:
	s_andn2_saveexec_b64 s[12:13], s[12:13]
	s_cbranch_execz .LBB0_786
	s_add_i32 s101, s101, 1
	v_mov_b32_e32 v1, s54
	v_add_co_u32_e32 v2, vcc, 0x3000, v1
	v_mov_b32_e32 v1, s55
	buffer_wbl2 sc1
	s_waitcnt vmcnt(0)
	v_addc_co_u32_e32 v3, vcc, 0, v1, vcc
	flat_atomic_add v1, v[2:3], v228 offset:1024 sc0
	v_cvt_f32_u32_e32 v2, v0
	v_sub_u32_e32 v3, 0, v0
	s_add_u32 s14, s54, 0x3400
	s_addc_u32 s15, s55, 0
	v_rcp_iflag_f32_e32 v2, v2
	s_mov_b64 s[18:19], 0
	v_mul_f32_e32 v2, 0x4f7ffffe, v2
	v_cvt_u32_f32_e32 v2, v2
	v_mul_lo_u32 v3, v3, v2
	v_mul_hi_u32 v3, v2, v3
	v_add_u32_e32 v2, v2, v3
	s_waitcnt vmcnt(0) lgkmcnt(0)
	v_mul_hi_u32 v2, v1, v2
	v_mul_lo_u32 v3, v2, v0
	v_sub_u32_e32 v3, v1, v3
	v_cmp_ge_u32_e32 vcc, v3, v0
	v_add_u32_e32 v4, 1, v2
	s_nop 0
	v_cndmask_b32_e32 v2, v2, v4, vcc
	v_sub_u32_e32 v4, v3, v0
	v_cndmask_b32_e32 v3, v3, v4, vcc
	v_cmp_ge_u32_e32 vcc, v3, v0
	v_add_u32_e32 v3, 1, v2
	s_nop 0
	v_cndmask_b32_e32 v2, v2, v3, vcc
	v_add_u32_e32 v3, 1, v1
	v_mad_u64_u32 v[0:1], s[8:9], v0, v2, v[0:1]
	v_cmp_ne_u32_e32 vcc, v3, v0
	v_mov_b32_e32 v3, v0
	v_mov_b64_e32 v[0:1], s[14:15]
	s_and_saveexec_b64 s[16:17], vcc
	s_cbranch_execz .LBB0_783
	v_mov_b64_e32 v[0:1], s[14:15]
	flat_load_dword v0, v[0:1] sc1
	s_mov_b64 s[22:23], 0
	s_waitcnt vmcnt(0) lgkmcnt(0)
	v_cmp_lt_u32_e32 vcc, v0, v3
	s_and_saveexec_b64 s[20:21], vcc
	s_cbranch_execz .LBB0_782
	s_add_u32 s18, s54, 0x200
	s_addc_u32 s19, s55, 0
	s_mov_b32 s7, 1
	s_branch .LBB0_775

.LBB0_785:
	s_or_b64 exec, exec, s[14:15]
	s_add_i32 s82, s6, 0x900
	s_lshl_b64 s[6:7], s[82:83], 2
	s_add_u32 s6, s54, s6
	s_addc_u32 s7, s55, s7
	v_mov_b64_e32 v[0:1], s[6:7]
	s_waitcnt vmcnt(0) lgkmcnt(0)
	s_nop 0
	global_atomic_add v[0:1], v228, off
	s_nop 0

.LBB0_890:
	s_andn2_saveexec_b64 s[8:9], s[12:13]
	s_cbranch_execz .LBB0_906
	s_add_i32 s101, s101, 1
	v_mov_b32_e32 v1, s54
	v_add_co_u32_e32 v2, vcc, 0x3000, v1
	v_mov_b32_e32 v1, s55
	buffer_wbl2 sc1
	s_waitcnt vmcnt(0)
	v_addc_co_u32_e32 v3, vcc, 0, v1, vcc
	flat_atomic_add v1, v[2:3], v228 offset:1024 sc0
	v_cvt_f32_u32_e32 v2, v0
	v_sub_u32_e32 v3, 0, v0
	s_add_u32 s12, s54, 0x3400
	s_addc_u32 s13, s55, 0
	v_rcp_iflag_f32_e32 v2, v2
	s_mov_b64 s[16:17], 0
	v_mul_f32_e32 v2, 0x4f7ffffe, v2
	v_cvt_u32_f32_e32 v2, v2
	v_mul_lo_u32 v3, v3, v2
	v_mul_hi_u32 v3, v2, v3
	v_add_u32_e32 v2, v2, v3
	s_waitcnt vmcnt(0) lgkmcnt(0)
	v_mul_hi_u32 v2, v1, v2
	v_mul_lo_u32 v3, v2, v0
	v_sub_u32_e32 v3, v1, v3
	v_cmp_ge_u32_e32 vcc, v3, v0
	v_add_u32_e32 v4, 1, v2
	s_nop 0
	v_cndmask_b32_e32 v2, v2, v4, vcc
	v_sub_u32_e32 v4, v3, v0
	v_cndmask_b32_e32 v3, v3, v4, vcc
	v_cmp_ge_u32_e32 vcc, v3, v0
	v_add_u32_e32 v3, 1, v2
	s_nop 0
	v_cndmask_b32_e32 v2, v2, v3, vcc
	v_add_u32_e32 v3, 1, v1
	v_mad_u64_u32 v[0:1], s[8:9], v0, v2, v[0:1]
	v_cmp_ne_u32_e32 vcc, v3, v0
	v_mov_b32_e32 v3, v0
	v_mov_b64_e32 v[0:1], s[12:13]
	s_and_saveexec_b64 s[14:15], vcc
	s_cbranch_execz .LBB0_903
	v_mov_b64_e32 v[0:1], s[12:13]
	flat_load_dword v0, v[0:1] sc1
	s_mov_b64 s[20:21], 0
	s_waitcnt vmcnt(0) lgkmcnt(0)
	v_cmp_lt_u32_e32 vcc, v0, v3
	s_and_saveexec_b64 s[18:19], vcc
	s_cbranch_execz .LBB0_902
	s_add_u32 s16, s54, 0x200
	s_addc_u32 s17, s55, 0
	s_mov_b32 s7, 1
	s_branch .LBB0_895

.LBB0_905:
	s_or_b64 exec, exec, s[12:13]
	s_add_i32 s82, s6, 0x900
	s_lshl_b64 s[6:7], s[82:83], 2
	s_add_u32 s6, s54, s6
	s_addc_u32 s7, s55, s7
	v_mov_b64_e32 v[0:1], s[6:7]
	s_waitcnt vmcnt(0) lgkmcnt(0)
	s_nop 0
	global_atomic_add v[0:1], v228, off
	s_nop 0

.LBB0_1136:
	s_andn2_saveexec_b64 s[8:9], s[12:13]
	s_cbranch_execz .LBB0_1152
	s_add_i32 s101, s101, 1
	v_mov_b32_e32 v1, s50
	v_add_co_u32_e32 v2, vcc, 0x3000, v1
	v_mov_b32_e32 v1, s51
	buffer_wbl2 sc1
	s_waitcnt vmcnt(0)
	v_addc_co_u32_e32 v3, vcc, 0, v1, vcc
	flat_atomic_add v1, v[2:3], v228 offset:1024 sc0
	v_cvt_f32_u32_e32 v2, v0
	v_sub_u32_e32 v3, 0, v0
	s_add_u32 s12, s50, 0x3400
	s_addc_u32 s13, s51, 0
	v_rcp_iflag_f32_e32 v2, v2
	s_mov_b64 s[16:17], 0
	v_mul_f32_e32 v2, 0x4f7ffffe, v2
	v_cvt_u32_f32_e32 v2, v2
	v_mul_lo_u32 v3, v3, v2
	v_mul_hi_u32 v3, v2, v3
	v_add_u32_e32 v2, v2, v3
	s_waitcnt vmcnt(0) lgkmcnt(0)
	v_mul_hi_u32 v2, v1, v2
	v_mul_lo_u32 v3, v2, v0
	v_sub_u32_e32 v3, v1, v3
	v_cmp_ge_u32_e32 vcc, v3, v0
	v_add_u32_e32 v4, 1, v2
	s_nop 0
	v_cndmask_b32_e32 v2, v2, v4, vcc
	v_sub_u32_e32 v4, v3, v0
	v_cndmask_b32_e32 v3, v3, v4, vcc
	v_cmp_ge_u32_e32 vcc, v3, v0
	v_add_u32_e32 v3, 1, v2
	s_nop 0
	v_cndmask_b32_e32 v2, v2, v3, vcc
	v_add_u32_e32 v3, 1, v1
	v_mad_u64_u32 v[0:1], s[8:9], v0, v2, v[0:1]
	v_cmp_ne_u32_e32 vcc, v3, v0
	v_mov_b32_e32 v3, v0
	v_mov_b64_e32 v[0:1], s[12:13]
	s_and_saveexec_b64 s[14:15], vcc
	s_cbranch_execz .LBB0_1149
	v_mov_b64_e32 v[0:1], s[12:13]
	flat_load_dword v0, v[0:1] sc1
	s_mov_b64 s[20:21], 0
	s_waitcnt vmcnt(0) lgkmcnt(0)
	v_cmp_lt_u32_e32 vcc, v0, v3
	s_and_saveexec_b64 s[18:19], vcc
	s_cbranch_execz .LBB0_1148
	s_add_u32 s16, s50, 0x200
	s_addc_u32 s17, s51, 0
	s_mov_b32 s7, 1
	s_branch .LBB0_1141

.LBB0_1151:
	s_or_b64 exec, exec, s[12:13]
	s_add_i32 s82, s6, 0x900
	s_lshl_b64 s[6:7], s[82:83], 2
	s_add_u32 s6, s50, s6
	s_addc_u32 s7, s51, s7
	v_mov_b64_e32 v[0:1], s[6:7]
	s_waitcnt vmcnt(0) lgkmcnt(0)
	s_nop 0
	global_atomic_add v[0:1], v228, off
	s_nop 0

.LBB0_1251:
	s_andn2_saveexec_b64 s[8:9], s[10:11]
	s_cbranch_execz .LBB0_1267
	s_add_i32 s101, s101, 1
	v_mov_b32_e32 v1, s50
	v_add_co_u32_e32 v2, vcc, 0x3000, v1
	v_mov_b32_e32 v1, s51
	buffer_wbl2 sc1
	s_waitcnt vmcnt(0)
	v_addc_co_u32_e32 v3, vcc, 0, v1, vcc
	flat_atomic_add v1, v[2:3], v228 offset:1024 sc0
	v_cvt_f32_u32_e32 v2, v0
	v_sub_u32_e32 v3, 0, v0
	s_add_u32 s10, s50, 0x3400
	s_addc_u32 s11, s51, 0
	v_rcp_iflag_f32_e32 v2, v2
	s_mov_b64 s[14:15], 0
	v_mul_f32_e32 v2, 0x4f7ffffe, v2
	v_cvt_u32_f32_e32 v2, v2
	v_mul_lo_u32 v3, v3, v2
	v_mul_hi_u32 v3, v2, v3
	v_add_u32_e32 v2, v2, v3
	s_waitcnt vmcnt(0) lgkmcnt(0)
	v_mul_hi_u32 v2, v1, v2
	v_mul_lo_u32 v3, v2, v0
	v_sub_u32_e32 v3, v1, v3
	v_cmp_ge_u32_e32 vcc, v3, v0
	v_add_u32_e32 v4, 1, v2
	s_nop 0
	v_cndmask_b32_e32 v2, v2, v4, vcc
	v_sub_u32_e32 v4, v3, v0
	v_cndmask_b32_e32 v3, v3, v4, vcc
	v_cmp_ge_u32_e32 vcc, v3, v0
	v_add_u32_e32 v3, 1, v2
	s_nop 0
	v_cndmask_b32_e32 v2, v2, v3, vcc
	v_add_u32_e32 v3, 1, v1
	v_mad_u64_u32 v[0:1], s[8:9], v0, v2, v[0:1]
	v_cmp_ne_u32_e32 vcc, v3, v0
	v_mov_b32_e32 v3, v0
	v_mov_b64_e32 v[0:1], s[10:11]
	s_and_saveexec_b64 s[12:13], vcc
	s_cbranch_execz .LBB0_1264
	v_mov_b64_e32 v[0:1], s[10:11]
	flat_load_dword v0, v[0:1] sc1
	s_mov_b64 s[18:19], 0
	s_waitcnt vmcnt(0) lgkmcnt(0)
	v_cmp_lt_u32_e32 vcc, v0, v3
	s_and_saveexec_b64 s[16:17], vcc
	s_cbranch_execz .LBB0_1263
	s_add_u32 s14, s50, 0x200
	s_addc_u32 s15, s51, 0
	s_mov_b32 s7, 1
	s_branch .LBB0_1256

.LBB0_1266:
	s_or_b64 exec, exec, s[10:11]
	s_add_i32 s82, s6, 0x900
	s_lshl_b64 s[6:7], s[82:83], 2
	s_add_u32 s6, s50, s6
	s_addc_u32 s7, s51, s7
	v_mov_b64_e32 v[0:1], s[6:7]
	s_waitcnt vmcnt(0) lgkmcnt(0)
	s_nop 0
	global_atomic_add v[0:1], v228, off
	s_nop 0

.LBB0_1329:
	s_andn2_saveexec_b64 s[8:9], s[12:13]
	s_cbranch_execz .LBB0_1345
	s_cmp_eq_u32 s100, 0
	s_cbranch_scc1 .Lfl_6
	s_add_i32 s82, s6, 0x900
	s_lshl_b64 s[8:9], s[82:83], 2
	s_add_u32 s8, s54, s8
	s_addc_u32 s9, s55, s9
	v_mov_b64_e32 v[0:1], s[8:9]
	global_atomic_add v[0:1], v228, off
	s_nop 0
	s_branch .LBB0_1345
.Lfl_6:
	s_add_i32 s101, s101, 1
	v_mov_b32_e32 v1, s54
	v_add_co_u32_e32 v2, vcc, 0x3000, v1
	v_mov_b32_e32 v1, s55
	buffer_wbl2 sc1
	s_waitcnt vmcnt(0)
	v_addc_co_u32_e32 v3, vcc, 0, v1, vcc
	flat_atomic_add v1, v[2:3], v228 offset:1024 sc0
	v_cvt_f32_u32_e32 v2, v0
	v_sub_u32_e32 v3, 0, v0
	s_add_u32 s12, s54, 0x3400
	s_addc_u32 s13, s55, 0
	v_rcp_iflag_f32_e32 v2, v2
	s_mov_b64 s[16:17], 0
	v_mul_f32_e32 v2, 0x4f7ffffe, v2
	v_cvt_u32_f32_e32 v2, v2
	v_mul_lo_u32 v3, v3, v2
	v_mul_hi_u32 v3, v2, v3
	v_add_u32_e32 v2, v2, v3
	s_waitcnt vmcnt(0) lgkmcnt(0)
	v_mul_hi_u32 v2, v1, v2
	v_mul_lo_u32 v3, v2, v0
	v_sub_u32_e32 v3, v1, v3
	v_cmp_ge_u32_e32 vcc, v3, v0
	v_add_u32_e32 v4, 1, v2
	s_nop 0
	v_cndmask_b32_e32 v2, v2, v4, vcc
	v_sub_u32_e32 v4, v3, v0
	v_cndmask_b32_e32 v3, v3, v4, vcc
	v_cmp_ge_u32_e32 vcc, v3, v0
	v_add_u32_e32 v3, 1, v2
	s_nop 0
	v_cndmask_b32_e32 v2, v2, v3, vcc
	v_add_u32_e32 v3, 1, v1
	v_mad_u64_u32 v[0:1], s[8:9], v0, v2, v[0:1]
	v_cmp_ne_u32_e32 vcc, v3, v0
	v_mov_b32_e32 v3, v0
	v_mov_b64_e32 v[0:1], s[12:13]
	s_and_saveexec_b64 s[14:15], vcc
	s_cbranch_execz .LBB0_1342
	v_mov_b64_e32 v[0:1], s[12:13]
	flat_load_dword v0, v[0:1] sc1
	s_mov_b64 s[20:21], 0
	s_waitcnt vmcnt(0) lgkmcnt(0)
	v_cmp_lt_u32_e32 vcc, v0, v3
	s_and_saveexec_b64 s[18:19], vcc
	s_cbranch_execz .LBB0_1341
	s_add_u32 s16, s54, 0x200
	s_addc_u32 s17, s55, 0
	s_mov_b32 s7, 1
	s_branch .LBB0_1334

.LBB0_1344:
	s_or_b64 exec, exec, s[12:13]
	s_add_i32 s82, s6, 0x900
	s_lshl_b64 s[6:7], s[82:83], 2
	s_add_u32 s6, s54, s6
	s_addc_u32 s7, s55, s7
	v_mov_b64_e32 v[0:1], s[6:7]
	s_waitcnt vmcnt(0) lgkmcnt(0)
	buffer_inv sc1
	global_atomic_add v[0:1], v228, off
	s_nop 0

.LBB0_1402:
	s_cmp_eq_u32 s100, 0
	s_cbranch_scc1 .Lfl_7
	s_add_i32 s82, s6, 0x900
	s_lshl_b64 s[10:11], s[82:83], 2
	s_add_u32 s10, s42, s10
	s_addc_u32 s11, s43, s11
	v_mov_b64_e32 v[0:1], s[10:11]
	global_atomic_add v[0:1], v228, off
	s_nop 0
	s_branch .Ltramp_7
